# phase X sliding-window items also use the hand-written LDS-staged attention loop
# speedup vs baseline: 1.0163x; 1.0054x over previous
; #define TIDX get_tid_()
; DI void nsa_win_item(const Params& p, int b, int head, int qb, const unsigned char* blut, const float* tbl) {
;   const int lane = TIDX & 63, r = lane & 31, h = lane >> 5;
;   const int g = head / 3, bg = b * 2 + g;
;   const int t = qb * 32 + r;
;   const float* tblh = tbl + head * 32;
;   bf16x8 qf[4];
;   load_q(qf, (const bf16_t*)(p.ws + OFF_QN) + (size_t)(b * 4096 + t) * 384 + head * 64 + 8 * h);
;   const float g2 = ((const float*)(p.ws + OFF_GATES))[(size_t)(b * 4096 + t) * 18 + head * 3 + 2];
;   f32x16 y0, y1;
; #pragma unroll
;   for (int i = 0; i < 16; ++i) { y0[i] = 0.f; y1[i] = 0.f; }
;   {
;     const bf16_t* K = (const bf16_t*)(p.ws + OFF_KWIN) + (size_t)bg * 4096 * 64;
;     const bf16_t* Vt = (const bf16_t*)(p.ws + OFF_VWINT) + (size_t)bg * 64 * 4096;
;     AttnSt st; attn_init(st);
;     const int k0 = qb >= 16 ? qb - 16 : 0;
;     attn_loop(st, qf, k0, qb, 32,
;     ...
;     else { const int it2 = item - 2048, qb = 31 - it2 / 48, sub = it2 % 48; nsa_win_item(p, sub / 6, sub % 6, qb, blut, tbl); }
.Lf6_done:
	v_mov_b32_e32 v2, s10
	s_movk_i32 s8, 0xe00
	s_waitcnt lgkmcnt(0)
	v_cmp_gt_i32_e32 vcc, s8, v2
	s_mov_b64 s[8:9], -1
	s_and_saveexec_b64 s[68:69], vcc
	s_cbranch_execz .LBB0_143
	s_movk_i32 s8, 0x7ff
	v_cmp_lt_i32_e32 vcc, s8, v2
	s_and_saveexec_b64 s[8:9], vcc
	s_xor_b64 s[8:9], exec, s[8:9]
	s_cbranch_execz .LBB0_158
	v_add_u16_e32 v0, 0xf800, v2
	v_mul_u32_u24_e32 v1, 0xaaab, v0
	v_lshrrev_b32_e32 v32, 21, v1
	v_mul_lo_u16_e32 v1, 48, v32
	v_sub_u16_e32 v0, v0, v1
	s_movk_i32 s10, 0xab
	v_mul_lo_u16_sdwa v1, v0, s10 dst_sel:DWORD dst_unused:UNUSED_PAD src0_sel:BYTE_0 src1_sel:DWORD
	v_lshrrev_b16_e32 v4, 10, v1
	v_mul_lo_u16_e32 v1, 6, v4
	v_sub_u16_e32 v33, v0, v1
	v_mov_b32_e32 v0, v129
	v_sub_u32_sdwa v138, v200, v32 dst_sel:DWORD dst_unused:UNUSED_PAD src0_sel:DWORD src1_sel:WORD_0
	v_readlane_b32 s10, v253, 13
	v_and_b32_e32 v34, 31, v0
	v_bfe_u32 v35, v0, 5, 1
	v_lshlrev_b32_e32 v0, 5, v138
	v_lshlrev_b32_e32 v1, 12, v4
	v_readlane_b32 s11, v253, 14
	v_or3_b32 v113, v34, v0, v1
	v_lshlrev_b32_sdwa v130, v202, v33 dst_sel:DWORD dst_unused:UNUSED_PAD src0_sel:DWORD src1_sel:BYTE_0
	v_mov_b64_e32 v[0:1], s[10:11]
	s_movk_i32 s10, 0x300
	v_mad_u64_u32 v[0:1], s[10:11], v113, s10, v[0:1]
	v_lshl_add_u64 v[0:1], v[0:1], 0, v[130:131]
	v_lshlrev_b32_e32 v2, 4, v35
	v_mov_b32_e32 v3, v131
	v_cmp_gt_u16_sdwa vcc, v33, v204 src0_sel:BYTE_0 src1_sel:DWORD
	v_lshl_add_u64 v[8:9], v[0:1], 0, v[2:3]
	v_readlane_b32 s10, v253, 31
	v_cndmask_b32_e32 v0, 0, v205, vcc
	v_add_u32_e32 v139, 0, v130
	v_lshl_or_b32 v130, v4, 20, v0
	v_readlane_b32 s11, v253, 32
	v_sub_u32_sdwa v36, v206, v32 clamp dst_sel:DWORD dst_unused:UNUSED_PAD src0_sel:DWORD src1_sel:WORD_0
	v_lshlrev_b32_e32 v2, 3, v34
	v_lshl_add_u64 v[24:25], s[10:11], 0, v[130:131]
	v_readlane_b32 s10, v253, 33
	v_readlane_b32 s11, v253, 34
	v_lshl_or_b32 v28, v35, 8, v2
	v_lshlrev_b32_e32 v30, 1, v28
	v_lshl_add_u64 v[26:27], s[10:11], 0, v[130:131]
	v_lshlrev_b32_e32 v130, 12, v36
	v_lshl_add_u64 v[0:1], v[24:25], 0, v[130:131]
	v_mov_b32_e32 v31, v131
	v_lshl_add_u64 v[10:11], v[0:1], 0, v[30:31]
	global_load_dwordx4 v[0:3], v[10:11], off
	global_load_dwordx4 v[64:67], v[8:9], off
	v_readlane_b32 s10, v253, 29
	v_readlane_b32 s11, v253, 30
	v_mul_u32_u24_sdwa v6, v33, v203 dst_sel:DWORD dst_unused:UNUSED_PAD src0_sel:BYTE_0 src1_sel:DWORD
	v_lshlrev_b32_e32 v14, 2, v6
	v_mov_b64_e32 v[4:5], s[10:11]
	s_movk_i32 s10, 0x48
	v_mad_u64_u32 v[12:13], s[10:11], v113, s10, v[4:5]
	global_load_dwordx4 v[4:7], v[10:11], off offset:1024
	v_mov_b32_e32 v15, v131
	v_lshl_add_u64 v[12:13], v[12:13], 0, v[14:15]
	global_load_dword v140, v[12:13], off
	global_load_dwordx4 v[68:71], v[8:9], off offset:32
	global_load_dwordx4 v[72:75], v[8:9], off offset:64
	global_load_dwordx4 v[76:79], v[8:9], off offset:96
	global_load_dwordx4 v[16:19], v[10:11], off offset:2048
	global_load_dwordx4 v[20:23], v[10:11], off offset:3072
	v_add_u32_e32 v8, 1, v36
	v_cmp_lt_u32_e32 vcc, v36, v138
	v_mov_b32_e32 v9, v131
	v_mov_b32_e32 v29, v131
	v_cndmask_b32_e32 v8, v138, v8, vcc
	v_lshlrev_b32_e32 v8, 12, v8
	v_lshl_add_u64 v[8:9], v[24:25], 0, v[8:9]
	v_lshl_add_u64 v[10:11], v[26:27], 0, v[130:131]
	v_lshl_add_u64 v[8:9], v[8:9], 0, v[30:31]
	v_lshl_add_u64 v[10:11], v[10:11], 0, v[28:29]
	global_load_dwordx4 v[88:91], v[8:9], off offset:2048
	global_load_dwordx4 v[80:83], v[8:9], off offset:1024
	global_load_dwordx4 v[92:95], v[8:9], off
	global_load_dwordx2 v[86:87], v[10:11], off offset:3584
	global_load_dwordx2 v[84:85], v[10:11], off offset:3072
	global_load_dwordx2 v[102:103], v[10:11], off offset:2560
	global_load_dwordx2 v[100:101], v[10:11], off offset:2048
	global_load_dwordx2 v[106:107], v[10:11], off offset:1536
	global_load_dwordx2 v[104:105], v[10:11], off offset:1024
	global_load_dwordx2 v[110:111], v[10:11], off offset:512
	global_load_dwordx4 v[96:99], v[8:9], off offset:3072
	global_load_dwordx2 v[108:109], v[10:11], off
	s_mov_b32 s53, s52
	v_lshlrev_b32_e32 v141, 2, v35
	s_mov_b32 s54, s52
	s_mov_b32 s55, s52
	s_mov_b32 s56, s52
	s_mov_b32 s57, s52
	s_mov_b32 s58, s52
	s_mov_b32 s59, s52
	s_mov_b32 s60, s52
	s_mov_b32 s61, s52
	s_mov_b32 s62, s52
	s_mov_b32 s63, s52
	s_mov_b32 s64, s52
	s_mov_b32 s65, s52
	s_mov_b32 s66, s52
	s_mov_b32 s67, s52
	v_lshl_add_u64 v[114:115], v[26:27], 0, v[28:29]
	v_lshl_add_u64 v[116:117], v[24:25], 0, v[30:31]
	v_lshlrev_b32_sdwa v112, v201, v33 dst_sel:DWORD dst_unused:UNUSED_PAD src0_sel:DWORD src1_sel:BYTE_0
	v_mov_b32_e32 v145, 0
	v_mov_b32_e32 v146, 0xff800000
	s_mov_b64 s[10:11], 0
	s_waitcnt vmcnt(19)
	v_mfma_f32_32x32x16_bf16 v[48:63], v[0:3], v[64:67], 0
	s_waitcnt vmcnt(16)
	v_mfma_f32_32x32x16_bf16 v[48:63], v[4:7], v[68:71], v[48:63]
	v_mov_b64_e32 v[0:1], s[52:53]
	v_mov_b64_e32 v[14:15], s[66:67]
	v_mov_b64_e32 v[2:3], s[54:55]
	v_mov_b64_e32 v[4:5], s[56:57]
	v_mov_b64_e32 v[6:7], s[58:59]
	v_mov_b64_e32 v[8:9], s[60:61]
	v_mov_b64_e32 v[10:11], s[62:63]
	s_waitcnt vmcnt(13)
	v_mfma_f32_32x32x16_bf16 v[48:63], v[16:19], v[72:75], v[48:63]
	v_min_u32_sdwa v16, v32, v206 dst_sel:DWORD dst_unused:UNUSED_PAD src0_sel:WORD_0 src1_sel:DWORD
	v_lshl_or_b32 v17, v16, 5, v34
	v_sub_u32_e32 v17, v17, v141
	v_lshlrev_b32_sdwa v18, v207, v32 dst_sel:DWORD dst_unused:UNUSED_PAD src0_sel:DWORD src1_sel:WORD_0
	v_sub_u32_e32 v17, v17, v18
	v_mov_b64_e32 v[12:13], s[64:65]
	v_add_u32_e32 v142, 0x1e5, v17
	s_waitcnt vmcnt(12)
	v_mfma_f32_32x32x16_bf16 v[48:63], v[20:23], v[76:79], v[48:63]
	v_sub_u32_e32 v143, 17, v16
	v_mov_b64_e32 v[30:31], v[14:15]
	v_mov_b64_e32 v[28:29], v[12:13]
	v_mov_b64_e32 v[26:27], v[10:11]
	v_mov_b64_e32 v[24:25], v[8:9]
	v_mov_b64_e32 v[22:23], v[6:7]
	v_mov_b64_e32 v[20:21], v[4:5]
	v_mov_b64_e32 v[18:19], v[2:3]
	v_mov_b64_e32 v[16:17], v[0:1]
	s_waitcnt vmcnt(0)
	v_readfirstlane_b32 s60, v138
	v_lshrrev_b32_e32 v246, 6, v129
	v_and_b32_e32 v247, 63, v129
	v_lshlrev_b32_e32 v247, 3, v247
	v_readfirstlane_b32 s58, v246
	s_sub_u32 s65, s60, 16
	s_cmp_lt_u32 s60, 16
	s_cselect_b32 s65, 0, s65
	s_mov_b64 s[62:63], -1
	v_mov_b32_e32 v223, 0xff800000
	v_and_b32_e32 v222, 31, v129
	v_bfe_u32 v240, v129, 5, 1
	v_lshlrev_b32_e32 v240, 2, v240
	v_sub_u32_e32 v222, v222, v240
	v_mov_b32_e32 v32, s60
	v_mov_b32_e32 v33, 0x1940
	v_lshl_add_u32 v42, v246, 2, v33
	ds_write_b32 v42, v32
	s_waitcnt lgkmcnt(0)
	s_barrier
; #define MFMA32(a, b, c) __builtin_amdgcn_mfma_f32_32x32x16_bf16((a), (b), (c), 0, 0, 0)
; template <class KP, class VP, class ACT, class FILL>
; DI void attn_loop(AttnSt& st, const bf16x8 (&qf)[4], int k0, int k1, size_t vstride, KP kp, VP vp, ACT act, FILL fill) {
;     ...
;   for (int kt = k0; kt <= k1; ++kt) {
;     const int kn = (kt < k1) ? kt + 1 : k1;
;     const int kn2 = (kt + 2 <= k1) ? kt + 2 : k1;
;     {
;       const bf16_t* v0 = vp(kn);
; #pragma unroll
;       for (int j = 0; j < 8; ++j) nxt.v[j] = *(const s16x4*)(v0 + 256 * j);
;     }
;     bf16x8 k2[4];
;     {
;       const bf16_t* krow = kp(kn2);
; #pragma unroll
;       for (int ss = 0; ss < 4; ++ss) k2[ss] = *(const bf16x8*)(krow + 512 * ss);
;     }
;     f32x16 s_next;
; #pragma unroll
;     for (int i = 0; i < 16; ++i) s_next[i] = 0.f;
; #pragma unroll
;     for (int ss = 0; ss < 4; ++ss) s_next = MFMA32(nxt.k[ss], qf[ss], s_next);
; DI void bias16(const unsigned char* blut, const float* tblh, const int (&dist)[16], float (&bv)[16]) {
;   int bk[16];
; #pragma unroll
;   for (int i = 0; i < 16; ++i) { const int d = dist[i] < 0 ? 0 : (dist[i] > 2048 ? 2048 : dist[i]); bk[i] = blut[d]; }
; #pragma unroll
;   for (int i = 0; i < 16; ++i) asm volatile("" : "+v"(bk[i]));
; #pragma unroll
;   for (int i = 0; i < 16; ++i) bv[i] = tblh[bk[i]];
; #pragma unroll
;   for (int i = 0; i < 16; ++i) asm volatile("" : "+v"(bv[i]));
; }
	ds_read_b128 v[34:37], v33
	ds_read_b128 v[38:41], v33 offset:16
	s_waitcnt lgkmcnt(0)
	v_min3_u32 v42, v34, v35, v36
	v_min3_u32 v42, v42, v37, v38
	v_min3_u32 v42, v42, v39, v40
	v_min_u32_e32 v42, v42, v41
	v_max3_u32 v34, v34, v35, v36
	v_max3_u32 v34, v34, v37, v38
	v_max3_u32 v34, v34, v39, v40
	v_max_u32_e32 v34, v34, v41
	s_nop 0
	v_readfirstlane_b32 s59, v34
	v_readfirstlane_b32 s66, v42
	s_sub_u32 s56, s66, 16
	s_cmp_lt_u32 s66, 16
	s_cselect_b32 s56, 0, s56
	s_and_b32 s56, s56, -2
	s_lshr_b32 s23, s56, 1
	s_mov_b32 s64, 0x10000
	s_lshr_b32 s24, s59, 1
	s_min_u32 s24, s23, s24
	s_lshl_b32 s26, s24, 13
	s_lshl_b32 s24, s58, 10
	s_add_u32 s26, s26, s24
	s_mov_b32 s27, 0
	v_lshl_add_u64 v[248:249], v[116:117], 0, s[26:27]
	v_lshl_add_u64 v[250:251], v[114:115], 0, s[26:27]
	v_add_co_u32_e32 v250, vcc, v250, v247
	v_addc_co_u32_e32 v251, vcc, 0, v251, vcc
	s_add_u32 s24, s24, s64
	s_mov_b32 m0, s24
	s_nop 0
	global_load_lds_dwordx4 v[248:249], off
	s_add_u32 s24, s24, 0x2000
	s_mov_b32 m0, s24
	s_nop 0
	global_load_lds_dwordx4 v[250:251], off
	s_lshr_b32 s23, s56, 1
	s_add_u32 s23, s23, 1
	s_mov_b32 s64, 0x14000
	s_lshr_b32 s24, s59, 1
	s_min_u32 s24, s23, s24
	s_lshl_b32 s26, s24, 13
	s_lshl_b32 s24, s58, 10
	s_add_u32 s26, s26, s24
	s_mov_b32 s27, 0
	v_lshl_add_u64 v[248:249], v[116:117], 0, s[26:27]
	v_lshl_add_u64 v[250:251], v[114:115], 0, s[26:27]
	v_add_co_u32_e32 v250, vcc, v250, v247
	v_addc_co_u32_e32 v251, vcc, 0, v251, vcc
	s_add_u32 s24, s24, s64
	s_mov_b32 m0, s24
	s_nop 0
	global_load_lds_dwordx4 v[248:249], off
	s_add_u32 s24, s24, 0x2000
	s_mov_b32 m0, s24
	s_nop 0
	global_load_lds_dwordx4 v[250:251], off
	s_mov_b32 s64, 0x10000
	v_lshrrev_b32_e32 v246, 6, v129
	v_mul_u32_u24_e32 v246, 6912, v246
	v_add_u32_e32 v242, 8192, v246
	v_and_b32_e32 v246, 63, v129
	v_mov_b32_e32 v80, 0
	v_mov_b32_e32 v81, v246
	v_add_u32_e32 v82, 64, v246
	v_add_u32_e32 v83, 128, v246
	v_add_u32_e32 v84, 192, v246
	v_add_u32_e32 v85, 256, v246
	v_add_u32_e32 v86, 320, v246
	v_add_u32_e32 v87, 384, v246
	v_add_u32_e32 v88, 448, v246
	v_add_u32_e32 v89, 512, v246
	ds_read_u8 v80, v80
	ds_read_u8 v81, v81
	ds_read_u8 v82, v82
	ds_read_u8 v83, v83
	ds_read_u8 v84, v84
	ds_read_u8 v85, v85
	ds_read_u8 v86, v86
	ds_read_u8 v87, v87
	ds_read_u8 v88, v88
	ds_read_u8 v89, v89
	s_waitcnt lgkmcnt(9)
	v_lshl_add_u32 v80, v80, 2, v139
	s_waitcnt lgkmcnt(8)
	v_lshl_add_u32 v81, v81, 2, v139
	s_waitcnt lgkmcnt(7)
	v_lshl_add_u32 v82, v82, 2, v139
	s_waitcnt lgkmcnt(6)
	v_lshl_add_u32 v83, v83, 2, v139
	s_waitcnt lgkmcnt(5)
	v_lshl_add_u32 v84, v84, 2, v139
	s_waitcnt lgkmcnt(4)
	v_lshl_add_u32 v85, v85, 2, v139
	s_waitcnt lgkmcnt(3)
	v_lshl_add_u32 v86, v86, 2, v139
	s_waitcnt lgkmcnt(2)
	v_lshl_add_u32 v87, v87, 2, v139
	s_waitcnt lgkmcnt(1)
	v_lshl_add_u32 v88, v88, 2, v139
	s_waitcnt lgkmcnt(0)
	v_lshl_add_u32 v89, v89, 2, v139
	ds_read_b32 v80, v80 offset:4096
	ds_read_b32 v81, v81 offset:4096
	ds_read_b32 v82, v82 offset:4096
	ds_read_b32 v83, v83 offset:4096
	ds_read_b32 v84, v84 offset:4096
	ds_read_b32 v85, v85 offset:4096
	ds_read_b32 v86, v86 offset:4096
	ds_read_b32 v87, v87 offset:4096
	ds_read_b32 v88, v88 offset:4096
	ds_read_b32 v89, v89 offset:4096
	v_lshl_add_u32 v244, v246, 2, v242
	s_waitcnt lgkmcnt(0)
	ds_write_b32 v244, v80 offset:0
	s_waitcnt lgkmcnt(0)
	ds_write_b32 v244, v81 offset:256
	s_waitcnt lgkmcnt(0)
	ds_write_b32 v244, v82 offset:512
	s_waitcnt lgkmcnt(0)
	ds_write_b32 v244, v83 offset:768
	s_waitcnt lgkmcnt(0)
	ds_write_b32 v244, v84 offset:1024
	s_waitcnt lgkmcnt(0)
	ds_write_b32 v244, v85 offset:1280
	s_waitcnt lgkmcnt(0)
	ds_write_b32 v244, v86 offset:1536
	s_waitcnt lgkmcnt(0)
	ds_write_b32 v244, v87 offset:1792
	s_waitcnt lgkmcnt(0)
	ds_write_b32 v244, v88 offset:2048
	s_waitcnt lgkmcnt(0)
	ds_write_b32 v244, v89 offset:2304
	ds_read_b32 v240, v139 offset:4220
	v_add_u32_e32 v242, 148, v242
	v_mov_b32_e32 v243, 0x7f800000
	s_waitcnt lgkmcnt(0)
.Lawin6_loop:
	s_waitcnt vmcnt(2)
	s_barrier
	s_lshr_b32 s23, s56, 1
	s_add_u32 s23, s23, 2
	s_sub_u32 s61, s64, 0x4000
	s_cmp_lt_u32 s61, 0x10000
	s_cselect_b32 s61, 0x18000, s61
	s_lshr_b32 s24, s59, 1
	s_min_u32 s24, s23, s24
	s_lshl_b32 s26, s24, 13
	s_lshl_b32 s24, s58, 10
	s_add_u32 s26, s26, s24
	s_mov_b32 s27, 0
	v_lshl_add_u64 v[248:249], v[116:117], 0, s[26:27]
	v_lshl_add_u64 v[250:251], v[114:115], 0, s[26:27]
	v_add_co_u32_e32 v250, vcc, v250, v247
	v_addc_co_u32_e32 v251, vcc, 0, v251, vcc
	s_add_u32 s24, s24, s61
	s_mov_b32 m0, s24
	s_nop 0
	global_load_lds_dwordx4 v[248:249], off
	s_add_u32 s24, s24, 0x2000
	s_mov_b32 m0, s24
	s_nop 0
	global_load_lds_dwordx4 v[250:251], off
	s_cmp_le_u32 s56, s60
	s_cbranch_scc0 .Lawin6_skip
	s_add_u32 s24, s56, 1
	s_cmp_ge_u32 s24, s65
	s_cbranch_scc0 .Lawin6_skip
	v_lshl_add_u32 v248, v247, 1, s64
	ds_read_b128 v[80:83], v248 offset:0
	ds_read_b128 v[84:87], v248 offset:1024
	ds_read_b128 v[88:91], v248 offset:2048
	ds_read_b128 v[92:95], v248 offset:3072
	ds_read_b128 v[96:99], v248 offset:4096
	ds_read_b128 v[100:103], v248 offset:5120
	ds_read_b128 v[104:107], v248 offset:6144
	ds_read_b128 v[108:111], v248 offset:7168
	s_sub_i32 s61, s60, s56
	s_waitcnt lgkmcnt(0)
	v_mfma_f32_32x32x16_bf16 v[32:47], v[80:83], v[64:67], 0
	v_mfma_f32_32x32x16_bf16 v[48:63], v[96:99], v[64:67], 0
	v_mfma_f32_32x32x16_bf16 v[32:47], v[84:87], v[68:71], v[32:47]
	v_mfma_f32_32x32x16_bf16 v[48:63], v[100:103], v[68:71], v[48:63]
	v_mfma_f32_32x32x16_bf16 v[32:47], v[88:91], v[72:75], v[32:47]
	v_mfma_f32_32x32x16_bf16 v[48:63], v[104:107], v[72:75], v[48:63]
	v_mfma_f32_32x32x16_bf16 v[32:47], v[92:95], v[76:79], v[32:47]
	v_mfma_f32_32x32x16_bf16 v[48:63], v[108:111], v[76:79], v[48:63]
	v_add_u32_e32 v250, s64, v247
	ds_read_b64 v[146:147], v250 offset:8192
	ds_read_b64 v[148:149], v250 offset:8704
	ds_read_b64 v[150:151], v250 offset:9216
	ds_read_b64 v[152:153], v250 offset:9728
	ds_read_b64 v[154:155], v250 offset:10240
	ds_read_b64 v[156:157], v250 offset:10752
	ds_read_b64 v[158:159], v250 offset:11264
	ds_read_b64 v[160:161], v250 offset:11776
	ds_read_b64 v[162:163], v250 offset:12288
	ds_read_b64 v[164:165], v250 offset:12800
	ds_read_b64 v[166:167], v250 offset:13312
	ds_read_b64 v[168:169], v250 offset:13824
	ds_read_b64 v[170:171], v250 offset:14336
	ds_read_b64 v[172:173], v250 offset:14848
	ds_read_b64 v[174:175], v250 offset:15360
	ds_read_b64 v[176:177], v250 offset:15872
	s_cmp_ge_i32 s61, 50
	s_cbranch_scc1 .Lawin6_far
; #define NEGINF (-__builtin_inff())
; DI int crow(int i, int h) { return (i & 3) + 8 * (i >> 2) + 4 * h; }
; DI void nsa_win_item(const Params& p, int b, int head, int qb, const unsigned char* blut, const float* tbl) {
;     ...
;       [&](int kt, const f32x16& s, float (&lg)[16]) {
;         int dist[16]; float bv[16];
; #pragma unroll
;         for (int i = 0; i < 16; ++i) dist[i] = t - (kt * 32 + crow(i, h));
;         bias16(blut, tblh, dist, bv);
; #pragma unroll
;         for (int i = 0; i < 16; ++i) lg[i] = (dist[i] >= 0 && dist[i] < 512) ? s[i] + bv[i] : NEGINF;
	s_lshl_b32 s23, s61, 5
	v_add_u32_e32 v241, s23, v222
	v_lshl_add_u32 v244, v241, 2, v242
	v_subrev_u32_e32 v245, 128, v244
	ds_read_b32 v224, v244 offset:108
	ds_read_b32 v225, v244 offset:104
	ds_read_b32 v226, v244 offset:100
	ds_read_b32 v227, v244 offset:96
	ds_read_b32 v228, v244 offset:76
	ds_read_b32 v229, v244 offset:72
	ds_read_b32 v230, v244 offset:68
	ds_read_b32 v231, v244 offset:64
	ds_read_b32 v232, v244 offset:44
	ds_read_b32 v233, v244 offset:40
	ds_read_b32 v234, v244 offset:36
	ds_read_b32 v235, v244 offset:32
	ds_read_b32 v236, v244 offset:12
	ds_read_b32 v237, v244 offset:8
	ds_read_b32 v238, v244 offset:4
	ds_read_b32 v239, v244 offset:0
	s_waitcnt lgkmcnt(8)
	v_add_f32_e32 v32, v32, v224
	v_add_f32_e32 v33, v33, v225
	v_add_f32_e32 v34, v34, v226
	v_add_f32_e32 v35, v35, v227
	v_add_f32_e32 v36, v36, v228
	v_add_f32_e32 v37, v37, v229
	v_add_f32_e32 v38, v38, v230
	v_add_f32_e32 v39, v39, v231
	s_waitcnt lgkmcnt(0)
	v_add_f32_e32 v40, v40, v232
	v_add_f32_e32 v41, v41, v233
	v_add_f32_e32 v42, v42, v234
	v_add_f32_e32 v43, v43, v235
	v_add_f32_e32 v44, v44, v236
	v_add_f32_e32 v45, v45, v237
	v_add_f32_e32 v46, v46, v238
	v_add_f32_e32 v47, v47, v239
	ds_read_b32 v224, v245 offset:108
	ds_read_b32 v225, v245 offset:104
	ds_read_b32 v226, v245 offset:100
	ds_read_b32 v227, v245 offset:96
	ds_read_b32 v228, v245 offset:76
	ds_read_b32 v229, v245 offset:72
	ds_read_b32 v230, v245 offset:68
	ds_read_b32 v231, v245 offset:64
	ds_read_b32 v232, v245 offset:44
	ds_read_b32 v233, v245 offset:40
	ds_read_b32 v234, v245 offset:36
	ds_read_b32 v235, v245 offset:32
	ds_read_b32 v236, v245 offset:12
	ds_read_b32 v237, v245 offset:8
	ds_read_b32 v238, v245 offset:4
	ds_read_b32 v239, v245 offset:0
	s_waitcnt lgkmcnt(8)
	v_add_f32_e32 v48, v48, v224
	v_add_f32_e32 v49, v49, v225
	v_add_f32_e32 v50, v50, v226
	v_add_f32_e32 v51, v51, v227
	v_add_f32_e32 v52, v52, v228
	v_add_f32_e32 v53, v53, v229
	v_add_f32_e32 v54, v54, v230
	v_add_f32_e32 v55, v55, v231
	s_waitcnt lgkmcnt(0)
	v_add_f32_e32 v56, v56, v232
	v_add_f32_e32 v57, v57, v233
	v_add_f32_e32 v58, v58, v234
	v_add_f32_e32 v59, v59, v235
	v_add_f32_e32 v60, v60, v236
	v_add_f32_e32 v61, v61, v237
	v_add_f32_e32 v62, v62, v238
	v_add_f32_e32 v63, v63, v239
	s_cmp_ge_i32 s61, 15
	s_cbranch_scc0 .Lawin6_nowin
	v_subrev_u32_e32 v246, 32, v241
	v_cmp_gt_i32_e32 vcc, 0x200, v241
	s_nop 1
	v_cndmask_b32_e32 v32, v199, v32, vcc
	v_cmp_gt_i32_e32 vcc, 0x201, v241
	s_nop 1
	v_cndmask_b32_e32 v33, v199, v33, vcc
	v_cmp_gt_i32_e32 vcc, 0x202, v241
	s_nop 1
	v_cndmask_b32_e32 v34, v199, v34, vcc
	v_cmp_gt_i32_e32 vcc, 0x203, v241
	s_nop 1
	v_cndmask_b32_e32 v35, v199, v35, vcc
	v_cmp_gt_i32_e32 vcc, 0x208, v241
	s_nop 1
	v_cndmask_b32_e32 v36, v199, v36, vcc
	v_cmp_gt_i32_e32 vcc, 0x209, v241
	s_nop 1
	v_cndmask_b32_e32 v37, v199, v37, vcc
	v_cmp_gt_i32_e32 vcc, 0x20a, v241
	s_nop 1
	v_cndmask_b32_e32 v38, v199, v38, vcc
	v_cmp_gt_i32_e32 vcc, 0x20b, v241
	s_nop 1
	v_cndmask_b32_e32 v39, v199, v39, vcc
	v_cmp_gt_i32_e32 vcc, 0x210, v241
	s_nop 1
	v_cndmask_b32_e32 v40, v199, v40, vcc
	v_cmp_gt_i32_e32 vcc, 0x211, v241
	s_nop 1
	v_cndmask_b32_e32 v41, v199, v41, vcc
	v_cmp_gt_i32_e32 vcc, 0x212, v241
	s_nop 1
	v_cndmask_b32_e32 v42, v199, v42, vcc
	v_cmp_gt_i32_e32 vcc, 0x213, v241
	s_nop 1
	v_cndmask_b32_e32 v43, v199, v43, vcc
	v_cmp_gt_i32_e32 vcc, 0x218, v241
	s_nop 1
	v_cndmask_b32_e32 v44, v199, v44, vcc
	v_cmp_gt_i32_e32 vcc, 0x219, v241
	s_nop 1
	v_cndmask_b32_e32 v45, v199, v45, vcc
	v_cmp_gt_i32_e32 vcc, 0x21a, v241
	s_nop 1
	v_cndmask_b32_e32 v46, v199, v46, vcc
	v_cmp_gt_i32_e32 vcc, 0x21b, v241
	s_nop 1
	v_cndmask_b32_e32 v47, v199, v47, vcc
	v_cmp_gt_i32_e32 vcc, 0x200, v246
	s_nop 1
	v_cndmask_b32_e32 v48, v199, v48, vcc
	v_cmp_gt_i32_e32 vcc, 0x201, v246
	s_nop 1
	v_cndmask_b32_e32 v49, v199, v49, vcc
	v_cmp_gt_i32_e32 vcc, 0x202, v246
	s_nop 1
	v_cndmask_b32_e32 v50, v199, v50, vcc
	v_cmp_gt_i32_e32 vcc, 0x203, v246
	s_nop 1
	v_cndmask_b32_e32 v51, v199, v51, vcc
	v_cmp_gt_i32_e32 vcc, 0x208, v246
	s_nop 1
	v_cndmask_b32_e32 v52, v199, v52, vcc
	v_cmp_gt_i32_e32 vcc, 0x209, v246
	s_nop 1
	v_cndmask_b32_e32 v53, v199, v53, vcc
	v_cmp_gt_i32_e32 vcc, 0x20a, v246
	s_nop 1
	v_cndmask_b32_e32 v54, v199, v54, vcc
	v_cmp_gt_i32_e32 vcc, 0x20b, v246
	s_nop 1
	v_cndmask_b32_e32 v55, v199, v55, vcc
	v_cmp_gt_i32_e32 vcc, 0x210, v246
	s_nop 1
	v_cndmask_b32_e32 v56, v199, v56, vcc
	v_cmp_gt_i32_e32 vcc, 0x211, v246
	s_nop 1
	v_cndmask_b32_e32 v57, v199, v57, vcc
	v_cmp_gt_i32_e32 vcc, 0x212, v246
	s_nop 1
	v_cndmask_b32_e32 v58, v199, v58, vcc
	v_cmp_gt_i32_e32 vcc, 0x213, v246
	s_nop 1
	v_cndmask_b32_e32 v59, v199, v59, vcc
	v_cmp_gt_i32_e32 vcc, 0x218, v246
	s_nop 1
	v_cndmask_b32_e32 v60, v199, v60, vcc
	v_cmp_gt_i32_e32 vcc, 0x219, v246
	s_nop 1
	v_cndmask_b32_e32 v61, v199, v61, vcc
	v_cmp_gt_i32_e32 vcc, 0x21a, v246
	s_nop 1
	v_cndmask_b32_e32 v62, v199, v62, vcc
	v_cmp_gt_i32_e32 vcc, 0x21b, v246
	s_nop 1
	v_cndmask_b32_e32 v63, v199, v63, vcc
; #define NEGINF (-__builtin_inff())
; DI int crow(int i, int h) { return (i & 3) + 8 * (i >> 2) + 4 * h; }
; DI void nsa_win_item(const Params& p, int b, int head, int qb, const unsigned char* blut, const float* tbl) {
;     ...
;       [&](int kt, const f32x16& s, float (&lg)[16]) {
;         int dist[16]; float bv[16];
; #pragma unroll
;         for (int i = 0; i < 16; ++i) dist[i] = t - (kt * 32 + crow(i, h));
;         bias16(blut, tblh, dist, bv);
; #pragma unroll
;         for (int i = 0; i < 16; ++i) lg[i] = (dist[i] >= 0 && dist[i] < 512) ? s[i] + bv[i] : NEGINF;
.Lawin6_nowin:
	s_cmp_ge_i32 s61, 2
	s_cbranch_scc1 .Lawin6_softmax
	v_subrev_u32_e32 v246, 32, v241
	v_cmp_le_i32_e32 vcc, 0, v241
	s_nop 1
	v_cndmask_b32_e32 v32, v199, v32, vcc
	v_cmp_le_i32_e32 vcc, 1, v241
	s_nop 1
	v_cndmask_b32_e32 v33, v199, v33, vcc
	v_cmp_le_i32_e32 vcc, 2, v241
	s_nop 1
	v_cndmask_b32_e32 v34, v199, v34, vcc
	v_cmp_le_i32_e32 vcc, 3, v241
	s_nop 1
	v_cndmask_b32_e32 v35, v199, v35, vcc
	v_cmp_le_i32_e32 vcc, 8, v241
	s_nop 1
	v_cndmask_b32_e32 v36, v199, v36, vcc
	v_cmp_le_i32_e32 vcc, 9, v241
	s_nop 1
	v_cndmask_b32_e32 v37, v199, v37, vcc
	v_cmp_le_i32_e32 vcc, 10, v241
	s_nop 1
	v_cndmask_b32_e32 v38, v199, v38, vcc
	v_cmp_le_i32_e32 vcc, 11, v241
	s_nop 1
	v_cndmask_b32_e32 v39, v199, v39, vcc
	v_cmp_le_i32_e32 vcc, 16, v241
	s_nop 1
	v_cndmask_b32_e32 v40, v199, v40, vcc
	v_cmp_le_i32_e32 vcc, 17, v241
	s_nop 1
	v_cndmask_b32_e32 v41, v199, v41, vcc
	v_cmp_le_i32_e32 vcc, 18, v241
	s_nop 1
	v_cndmask_b32_e32 v42, v199, v42, vcc
	v_cmp_le_i32_e32 vcc, 19, v241
	s_nop 1
	v_cndmask_b32_e32 v43, v199, v43, vcc
	v_cmp_le_i32_e32 vcc, 24, v241
	s_nop 1
	v_cndmask_b32_e32 v44, v199, v44, vcc
	v_cmp_le_i32_e32 vcc, 25, v241
	s_nop 1
	v_cndmask_b32_e32 v45, v199, v45, vcc
	v_cmp_le_i32_e32 vcc, 26, v241
	s_nop 1
	v_cndmask_b32_e32 v46, v199, v46, vcc
	v_cmp_le_i32_e32 vcc, 27, v241
	s_nop 1
	v_cndmask_b32_e32 v47, v199, v47, vcc
	v_cmp_le_i32_e32 vcc, 0, v246
	s_nop 1
	v_cndmask_b32_e32 v48, v199, v48, vcc
	v_cmp_le_i32_e32 vcc, 1, v246
	s_nop 1
	v_cndmask_b32_e32 v49, v199, v49, vcc
	v_cmp_le_i32_e32 vcc, 2, v246
	s_nop 1
	v_cndmask_b32_e32 v50, v199, v50, vcc
	v_cmp_le_i32_e32 vcc, 3, v246
	s_nop 1
	v_cndmask_b32_e32 v51, v199, v51, vcc
	v_cmp_le_i32_e32 vcc, 8, v246
	s_nop 1
	v_cndmask_b32_e32 v52, v199, v52, vcc
	v_cmp_le_i32_e32 vcc, 9, v246
	s_nop 1
	v_cndmask_b32_e32 v53, v199, v53, vcc
	v_cmp_le_i32_e32 vcc, 10, v246
	s_nop 1
	v_cndmask_b32_e32 v54, v199, v54, vcc
	v_cmp_le_i32_e32 vcc, 11, v246
	s_nop 1
	v_cndmask_b32_e32 v55, v199, v55, vcc
	v_cmp_le_i32_e32 vcc, 16, v246
	s_nop 1
	v_cndmask_b32_e32 v56, v199, v56, vcc
	v_cmp_le_i32_e32 vcc, 17, v246
	s_nop 1
	v_cndmask_b32_e32 v57, v199, v57, vcc
	v_cmp_le_i32_e32 vcc, 18, v246
	s_nop 1
	v_cndmask_b32_e32 v58, v199, v58, vcc
	v_cmp_le_i32_e32 vcc, 19, v246
	s_nop 1
	v_cndmask_b32_e32 v59, v199, v59, vcc
	v_cmp_le_i32_e32 vcc, 24, v246
	s_nop 1
	v_cndmask_b32_e32 v60, v199, v60, vcc
	v_cmp_le_i32_e32 vcc, 25, v246
	s_nop 1
	v_cndmask_b32_e32 v61, v199, v61, vcc
	v_cmp_le_i32_e32 vcc, 26, v246
	s_nop 1
	v_cndmask_b32_e32 v62, v199, v62, vcc
	v_cmp_le_i32_e32 vcc, 27, v246
	s_nop 1
	v_cndmask_b32_e32 v63, v199, v63, vcc
	s_branch .Lawin6_softmax

; #define MFMA32(a, b, c) __builtin_amdgcn_mfma_f32_32x32x16_bf16((a), (b), (c), 0, 0, 0)
; #define NEGINF (-__builtin_inff())
; DI float shx32(float v) { const auto r = __builtin_amdgcn_permlane32_swap(__float_as_uint(v), __float_as_uint(v), false, false); return __uint_as_float((threadIdx.x & 32) ? r[0] : r[1]); }
; DI float ex2(float x) { return __builtin_amdgcn_exp2f(x); }
; DI unsigned pack2(float a, float b) { unsigned r; asm("v_cvt_pk_bf16_f32 %0, %1, %2" : "=v"(r) : "v"(a), "v"(b)); return r; }
; DI void softmax_step_r(AttnSt& st, const float (&lg)[16], const KVT& t) {
;   float mx = NEGINF;
; #pragma unroll
;   for (int i = 0; i < 16; ++i) mx = fmaxf(mx, lg[i]);
;   mx = fmaxf(mx, shx32(mx));
;   if (__ballot(mx > NEGINF) == 0ull) return;
;   const float mnew = fmaxf(st.m, mx);
;   const float muse = (mnew == NEGINF) ? 0.f : mnew;
;   const float alpha = ex2(st.m - muse);
;   float pr[16]; float rs = 0.f;
; #pragma unroll
;   for (int i = 0; i < 16; ++i) { pr[i] = ex2(lg[i] - muse); rs += pr[i]; }
;   st.l = st.l * alpha + rs;
;   if (__ballot(mnew != st.m) != 0ull) {
; #pragma unroll
;     for (int i = 0; i < 16; ++i) { st.o0[i] *= alpha; st.o1[i] *= alpha; }
;   }
;   st.m = mnew;
; #pragma unroll
;   for (int s2 = 0; s2 < 2; ++s2) {
;     u32x4 pk; pk.x = pack2(pr[8 * s2], pr[8 * s2 + 1]); pk.y = pack2(pr[8 * s2 + 2], pr[8 * s2 + 3]); pk.z = pack2(pr[8 * s2 + 4], pr[8 * s2 + 5]); pk.w = pack2(pr[8 * s2 + 6], pr[8 * s2 + 7]);
;     const bf16x8 pb = __builtin_bit_cast(bf16x8, pk);
;     const bf16x8 va0 = __builtin_shufflevector(t.v[s2 * 4 + 0], t.v[s2 * 4 + 1], 0, 1, 2, 3, 4, 5, 6, 7);
;     st.o0 = MFMA32(va0, pb, st.o0);
;     const bf16x8 va1 = __builtin_shufflevector(t.v[s2 * 4 + 2], t.v[s2 * 4 + 3], 0, 1, 2, 3, 4, 5, 6, 7);
;     st.o1 = MFMA32(va1, pb, st.o1);
;   }
; }
.Lawin6_softmax:
	v_max3_f32 v224, v32, v33, v34
	v_max3_f32 v225, v40, v41, v42
	v_max3_f32 v226, v48, v49, v50
	v_max3_f32 v227, v56, v57, v58
	v_max3_f32 v224, v224, v35, v36
	v_max3_f32 v225, v225, v43, v44
	v_max3_f32 v226, v226, v51, v52
	v_max3_f32 v227, v227, v59, v60
	v_max3_f32 v224, v224, v37, v38
	v_max3_f32 v225, v225, v45, v46
	v_max3_f32 v226, v226, v53, v54
	v_max3_f32 v227, v227, v61, v62
	v_max_f32_e32 v224, v224, v39
	v_max_f32_e32 v225, v225, v47
	v_max_f32_e32 v226, v226, v55
	v_max_f32_e32 v227, v227, v63
	v_max3_f32 v224, v224, v225, v226
	v_max_f32_e32 v224, v224, v227
	v_mov_b32_e32 v225, v224
	v_mov_b32_e32 v226, v224
	s_nop 1
	v_permlane32_swap_b32_e32 v225, v226
	v_cndmask_b32_e64 v225, v225, v226, s[12:13]
	v_max_f32_e32 v224, v224, v225
	v_cndmask_b32_e64 v224, v199, v224, s[62:63]
	v_max_f32_e32 v225, v223, v224
	v_cmp_neq_f32_e32 vcc, v199, v225
	s_nop 1
	v_cndmask_b32_e32 v226, 0, v225, vcc
	v_sub_f32_e32 v227, v223, v226
	v_exp_f32_e32 v227, v227
	v_cndmask_b32_e64 v226, v243, v226, s[62:63]
	v_cmp_neq_f32_e32 vcc, v223, v225
	v_mov_b32_e32 v223, v225
	v_sub_f32_e32 v32, v32, v226
	v_sub_f32_e32 v33, v33, v226
	v_sub_f32_e32 v34, v34, v226
	v_sub_f32_e32 v35, v35, v226
	v_sub_f32_e32 v36, v36, v226
	v_sub_f32_e32 v37, v37, v226
	v_sub_f32_e32 v38, v38, v226
	v_sub_f32_e32 v39, v39, v226
	v_sub_f32_e32 v40, v40, v226
	v_sub_f32_e32 v41, v41, v226
	v_sub_f32_e32 v42, v42, v226
	v_sub_f32_e32 v43, v43, v226
	v_sub_f32_e32 v44, v44, v226
	v_sub_f32_e32 v45, v45, v226
	v_sub_f32_e32 v46, v46, v226
	v_sub_f32_e32 v47, v47, v226
	v_sub_f32_e32 v48, v48, v226
	v_sub_f32_e32 v49, v49, v226
	v_sub_f32_e32 v50, v50, v226
	v_sub_f32_e32 v51, v51, v226
	v_sub_f32_e32 v52, v52, v226
	v_sub_f32_e32 v53, v53, v226
	v_sub_f32_e32 v54, v54, v226
	v_sub_f32_e32 v55, v55, v226
	v_sub_f32_e32 v56, v56, v226
	v_sub_f32_e32 v57, v57, v226
	v_sub_f32_e32 v58, v58, v226
	v_sub_f32_e32 v59, v59, v226
	v_sub_f32_e32 v60, v60, v226
	v_sub_f32_e32 v61, v61, v226
	v_sub_f32_e32 v62, v62, v226
	v_sub_f32_e32 v63, v63, v226
	v_exp_f32_e32 v32, v32
	v_exp_f32_e32 v33, v33
	v_exp_f32_e32 v34, v34
	v_exp_f32_e32 v35, v35
	v_exp_f32_e32 v36, v36
	v_exp_f32_e32 v37, v37
	v_exp_f32_e32 v38, v38
	v_exp_f32_e32 v39, v39
	v_exp_f32_e32 v40, v40
	v_exp_f32_e32 v41, v41
	v_exp_f32_e32 v42, v42
	v_exp_f32_e32 v43, v43
	v_exp_f32_e32 v44, v44
	v_exp_f32_e32 v45, v45
	v_exp_f32_e32 v46, v46
	v_exp_f32_e32 v47, v47
	v_exp_f32_e32 v48, v48
	v_exp_f32_e32 v49, v49
	v_exp_f32_e32 v50, v50
	v_exp_f32_e32 v51, v51
	v_exp_f32_e32 v52, v52
	v_exp_f32_e32 v53, v53
	v_exp_f32_e32 v54, v54
	v_exp_f32_e32 v55, v55
	v_exp_f32_e32 v56, v56
	v_exp_f32_e32 v57, v57
	v_exp_f32_e32 v58, v58
	v_exp_f32_e32 v59, v59
	v_exp_f32_e32 v60, v60
	v_exp_f32_e32 v61, v61
	v_exp_f32_e32 v62, v62
	v_exp_f32_e32 v63, v63
	v_add_f32_e32 v228, v32, v33
	v_add_f32_e32 v229, v40, v41
	v_add_f32_e32 v230, v48, v49
	v_add_f32_e32 v231, v56, v57
	v_add_f32_e32 v228, v228, v34
	v_add_f32_e32 v229, v229, v42
	v_add_f32_e32 v230, v230, v50
	v_add_f32_e32 v231, v231, v58
	v_add_f32_e32 v228, v228, v35
	v_add_f32_e32 v229, v229, v43
	v_add_f32_e32 v230, v230, v51
	v_add_f32_e32 v231, v231, v59
	v_add_f32_e32 v228, v228, v36
	v_add_f32_e32 v229, v229, v44
	v_add_f32_e32 v230, v230, v52
	v_add_f32_e32 v231, v231, v60
	v_add_f32_e32 v228, v228, v37
	v_add_f32_e32 v229, v229, v45
	v_add_f32_e32 v230, v230, v53
	v_add_f32_e32 v231, v231, v61
	v_add_f32_e32 v228, v228, v38
	v_add_f32_e32 v229, v229, v46
	v_add_f32_e32 v230, v230, v54
	v_add_f32_e32 v231, v231, v62
	v_add_f32_e32 v228, v228, v39
	v_add_f32_e32 v229, v229, v47
	v_add_f32_e32 v230, v230, v55
	v_add_f32_e32 v231, v231, v63
	v_add_f32_e32 v228, v228, v229
	v_add_f32_e32 v230, v230, v231
	v_add_f32_e32 v228, v228, v230
	v_fma_f32 v145, v145, v227, v228
	s_cbranch_vccz .Lawin6_noscale
	v_mul_f32_e32 v0, v227, v0
	v_mul_f32_e32 v1, v227, v1
	v_mul_f32_e32 v2, v227, v2
	v_mul_f32_e32 v3, v227, v3
	v_mul_f32_e32 v4, v227, v4
	v_mul_f32_e32 v5, v227, v5
	v_mul_f32_e32 v6, v227, v6
	v_mul_f32_e32 v7, v227, v7
	v_mul_f32_e32 v8, v227, v8
	v_mul_f32_e32 v9, v227, v9
	v_mul_f32_e32 v10, v227, v10
	v_mul_f32_e32 v11, v227, v11
	v_mul_f32_e32 v12, v227, v12
	v_mul_f32_e32 v13, v227, v13
	v_mul_f32_e32 v14, v227, v14
	v_mul_f32_e32 v15, v227, v15
	v_mul_f32_e32 v16, v227, v16
	v_mul_f32_e32 v17, v227, v17
	v_mul_f32_e32 v18, v227, v18
	v_mul_f32_e32 v19, v227, v19
	v_mul_f32_e32 v20, v227, v20
	v_mul_f32_e32 v21, v227, v21
	v_mul_f32_e32 v22, v227, v22
	v_mul_f32_e32 v23, v227, v23
	v_mul_f32_e32 v24, v227, v24
	v_mul_f32_e32 v25, v227, v25
	v_mul_f32_e32 v26, v227, v26
	v_mul_f32_e32 v27, v227, v27
	v_mul_f32_e32 v28, v227, v28
	v_mul_f32_e32 v29, v227, v29
	v_mul_f32_e32 v30, v227, v30
	v_mul_f32_e32 v31, v227, v31
; #define MFMA32(a, b, c) __builtin_amdgcn_mfma_f32_32x32x16_bf16((a), (b), (c), 0, 0, 0)
; DI float shx32(float v) { const auto r = __builtin_amdgcn_permlane32_swap(__float_as_uint(v), __float_as_uint(v), false, false); return __uint_as_float((threadIdx.x & 32) ? r[0] : r[1]); }
; DI unsigned pack2(float a, float b) { unsigned r; asm("v_cvt_pk_bf16_f32 %0, %1, %2" : "=v"(r) : "v"(a), "v"(b)); return r; }
; DI void softmax_step_r(AttnSt& st, const float (&lg)[16], const KVT& t) {
;     ...
;   for (int s2 = 0; s2 < 2; ++s2) {
;     u32x4 pk; pk.x = pack2(pr[8 * s2], pr[8 * s2 + 1]); pk.y = pack2(pr[8 * s2 + 2], pr[8 * s2 + 3]); pk.z = pack2(pr[8 * s2 + 4], pr[8 * s2 + 5]); pk.w = pack2(pr[8 * s2 + 6], pr[8 * s2 + 7]);
;     const bf16x8 pb = __builtin_bit_cast(bf16x8, pk);
;     const bf16x8 va0 = __builtin_shufflevector(t.v[s2 * 4 + 0], t.v[s2 * 4 + 1], 0, 1, 2, 3, 4, 5, 6, 7);
;     st.o0 = MFMA32(va0, pb, st.o0);
;     const bf16x8 va1 = __builtin_shufflevector(t.v[s2 * 4 + 2], t.v[s2 * 4 + 3], 0, 1, 2, 3, 4, 5, 6, 7);
;     st.o1 = MFMA32(va1, pb, st.o1);
;   }
; DI void nsa_win_item(const Params& p, int b, int head, int qb, const unsigned char* blut, const float* tbl) {
;     ...
;     float l = st.l + shx32(st.l);
;     const float sc = (l > 0.f) ? g2 / l : 0.f;
; #pragma unroll
;     for (int i = 0; i < 16; ++i) { y0[i] += sc * st.o0[i]; y1[i] += sc * st.o1[i]; }
;   }
;   store_o((bf16_t*)(p.ws + OFF_Y) + (size_t)(b * 4096 + t) * 768 + head * 64, y0, y1, h);
.Lawin6_noscale:
	v_cvt_pk_bf16_f32 v224, v32, v33
	v_cvt_pk_bf16_f32 v225, v34, v35
	v_cvt_pk_bf16_f32 v226, v36, v37
	v_cvt_pk_bf16_f32 v227, v38, v39
	v_cvt_pk_bf16_f32 v228, v40, v41
	v_cvt_pk_bf16_f32 v229, v42, v43
	v_cvt_pk_bf16_f32 v230, v44, v45
	v_cvt_pk_bf16_f32 v231, v46, v47
	v_cvt_pk_bf16_f32 v232, v48, v49
	v_cvt_pk_bf16_f32 v233, v50, v51
	v_cvt_pk_bf16_f32 v234, v52, v53
	v_cvt_pk_bf16_f32 v235, v54, v55
	v_cvt_pk_bf16_f32 v236, v56, v57
	v_cvt_pk_bf16_f32 v237, v58, v59
	v_cvt_pk_bf16_f32 v238, v60, v61
	v_cvt_pk_bf16_f32 v239, v62, v63
	s_waitcnt lgkmcnt(0)
	s_nop 1
	v_mfma_f32_32x32x16_bf16 v[0:15], v[146:149], v[224:227], v[0:15]
	v_mfma_f32_32x32x16_bf16 v[16:31], v[150:153], v[224:227], v[16:31]
	v_mfma_f32_32x32x16_bf16 v[0:15], v[154:157], v[228:231], v[0:15]
	v_mfma_f32_32x32x16_bf16 v[16:31], v[158:161], v[228:231], v[16:31]
	v_mfma_f32_32x32x16_bf16 v[0:15], v[162:165], v[232:235], v[0:15]
	v_mfma_f32_32x32x16_bf16 v[16:31], v[166:169], v[232:235], v[16:31]
	v_mfma_f32_32x32x16_bf16 v[0:15], v[170:173], v[236:239], v[0:15]
	v_mfma_f32_32x32x16_bf16 v[16:31], v[174:177], v[236:239], v[16:31]
.Lawin6_skip:
	s_add_u32 s64, s64, 0x4000
	s_cmp_eq_u32 s64, 0x1c000
	s_cselect_b32 s64, 0x10000, s64
	s_add_u32 s56, s56, 2
	s_cmp_le_u32 s56, s59
	s_cbranch_scc1 .Lawin6_loop
	s_nop 15
	s_waitcnt vmcnt(0)
.LBB0_157:
	s_or_b64 exec, exec, s[10:11]
	v_mov_b32_e32 v32, v145
	v_mov_b32_e32 v33, v145
	s_nop 1
	v_permlane32_swap_b32_e32 v32, v33
	v_cndmask_b32_e64 v32, v32, v33, s[12:13]
	v_add_f32_e32 v32, v145, v32
	v_div_scale_f32 v33, s[10:11], v32, v32, v140
	v_rcp_f32_e32 v34, v33
	v_readlane_b32 s10, v253, 19
	v_readlane_b32 s11, v253, 20
	v_lshlrev_b32_e32 v130, 1, v112
	v_fma_f32 v35, -v33, v34, 1.0
	v_fmac_f32_e32 v34, v35, v34
	v_div_scale_f32 v35, vcc, v140, v32, v140
	v_mul_f32_e32 v36, v35, v34
	v_fma_f32 v37, -v33, v36, v35
	v_fmac_f32_e32 v36, v37, v34
	v_fma_f32 v33, -v33, v36, v35
	v_div_fmas_f32 v33, v33, v34, v36
	v_div_fixup_f32 v33, v33, v32, v140
	v_cmp_lt_f32_e32 vcc, 0, v32
	s_mov_b32 s53, 0x8000
	s_nop 0
	v_cndmask_b32_e32 v32, 0, v33, vcc
	v_fma_f32 v33, v0, v32, 0
	v_fma_f32 v34, v1, v32, 0
	v_mov_b64_e32 v[0:1], s[10:11]
	s_movk_i32 s10, 0x600
	v_mad_u64_u32 v[0:1], s[10:11], v113, s10, v[0:1]
	v_lshl_add_u64 v[0:1], v[0:1], 0, v[130:131]
	v_lshlrev_b32_e32 v130, 1, v141
	v_fma_f32 v35, v2, v32, 0
	v_fma_f32 v3, v3, v32, 0
	v_lshl_add_u64 v[0:1], v[0:1], 0, v[130:131]
	v_cvt_pk_bf16_f32 v2, v33, v34
	v_fma_f32 v16, v16, v32, 0
	v_fma_f32 v17, v17, v32, 0
	v_cvt_pk_bf16_f32 v3, v35, v3
	global_store_dwordx2 v[0:1], v[2:3], off
	v_cvt_pk_bf16_f32 v2, v16, v17
	v_fma_f32 v18, v18, v32, 0
	v_fma_f32 v19, v19, v32, 0
	v_fma_f32 v4, v4, v32, 0
	v_fma_f32 v5, v5, v32, 0
	v_cvt_pk_bf16_f32 v3, v18, v19
	global_store_dwordx2 v[0:1], v[2:3], off offset:64
	v_cvt_pk_bf16_f32 v2, v4, v5
	v_fma_f32 v20, v20, v32, 0
	v_fma_f32 v21, v21, v32, 0
	v_fma_f32 v6, v6, v32, 0
	v_fma_f32 v7, v7, v32, 0
	v_cvt_pk_bf16_f32 v3, v6, v7
	global_store_dwordx2 v[0:1], v[2:3], off offset:16
	v_cvt_pk_bf16_f32 v2, v20, v21
	v_fma_f32 v22, v22, v32, 0
	v_fma_f32 v23, v23, v32, 0
	v_fma_f32 v8, v8, v32, 0
	v_fma_f32 v9, v9, v32, 0
	v_cvt_pk_bf16_f32 v3, v22, v23
	global_store_dwordx2 v[0:1], v[2:3], off offset:80
	v_cvt_pk_bf16_f32 v2, v8, v9
	v_fma_f32 v24, v24, v32, 0
	v_fma_f32 v25, v25, v32, 0
	v_fma_f32 v10, v10, v32, 0
	v_fma_f32 v11, v11, v32, 0
	v_cvt_pk_bf16_f32 v3, v10, v11
	global_store_dwordx2 v[0:1], v[2:3], off offset:32
	v_cvt_pk_bf16_f32 v2, v24, v25
	v_fma_f32 v26, v26, v32, 0
	v_fma_f32 v27, v27, v32, 0
	v_fma_f32 v12, v12, v32, 0
	v_fma_f32 v13, v13, v32, 0
	v_cvt_pk_bf16_f32 v3, v26, v27
	global_store_dwordx2 v[0:1], v[2:3], off offset:96
	v_cvt_pk_bf16_f32 v2, v12, v13
	v_fma_f32 v28, v28, v32, 0
	v_fma_f32 v29, v29, v32, 0
	v_fma_f32 v14, v14, v32, 0
	v_fma_f32 v15, v15, v32, 0
	v_cvt_pk_bf16_f32 v3, v14, v15
	global_store_dwordx2 v[0:1], v[2:3], off offset:48
	v_cvt_pk_bf16_f32 v2, v28, v29
	v_fma_f32 v30, v30, v32, 0
	v_fma_f32 v31, v31, v32, 0
	v_cvt_pk_bf16_f32 v3, v30, v31
	global_store_dwordx2 v[0:1], v[2:3], off offset:112
